# P1 barrier leader: release the XCD's waiters (XGEN bump) before its own cache invalidate
# speedup vs baseline: 1.0005x; 1.0005x over previous
.LBB0_388:
	s_andn2_saveexec_b64 s[8:9], s[8:9]
	s_cbranch_execz .LBB0_404
	s_cmp_eq_u32 s100, 0
	s_cbranch_scc1 .Lfl_1
	s_add_i32 s82, s6, 0x900
	s_lshl_b64 s[10:11], s[82:83], 2
	s_add_u32 s10, s42, s10
	s_addc_u32 s11, s43, s11
	v_mov_b64_e32 v[0:1], s[10:11]
	flat_atomic_add v[0:1], v228
	buffer_inv sc1
	s_waitcnt vmcnt(0)
	s_branch .LBB0_404
